# modulate phase: per row all 12 loads in flight with counted waits, input pointer hoisted out of the row loop
# baseline (speedup 1.0000x reference)
.LBB0_10:
	s_cmp_eq_u32 s54, 12
	v_readlane_b32 s2, v252, 12
	v_mov_b32_e32 v188, v191
	s_cselect_b64 s[0:1], -1, 0
	v_readlane_b32 s3, v252, 13
	v_readlane_b32 s42, v252, 0
	v_ashrrev_i32_e32 v190, 6, v188
	s_and_b64 s[0:1], s[2:3], s[0:1]
	v_readfirstlane_b32 s8, v190
	v_readlane_b32 s43, v252, 1
	s_and_b64 vcc, exec, s[0:1]
	s_cbranch_vccnz .LBB0_28
	s_load_dwordx4 s[12:15], s[42:43], 0x88
	v_readlane_b32 s0, v253, 42
	s_add_i32 s0, s8, s0
	v_and_b32_e32 v223, 63, v188
	v_writelane_b32 v254, s0, 0
	s_waitcnt lgkmcnt(0)
	s_add_u32 s2, s14, 0x3300000
	s_addc_u32 s3, s15, 0
	v_writelane_b32 v254, s1, 1
	s_add_u32 s0, s14, 0x100000
	s_addc_u32 s1, s15, 0
	v_writelane_b32 v254, s0, 2
	s_mov_b64 s[6:7], -1
	s_mov_b64 s[4:5], 0
	v_writelane_b32 v254, s1, 3
	s_add_u32 s0, s14, 0x128000
	s_addc_u32 s1, s15, 0
	v_writelane_b32 v254, s0, 4
	s_nop 1
	v_writelane_b32 v254, s1, 5
	s_add_u32 s0, s14, 0x12a000
	s_addc_u32 s1, s15, 0
	v_writelane_b32 v254, s0, 6
	s_nop 1
	v_writelane_b32 v254, s1, 7
	s_add_u32 s0, s14, 0x3500000
	v_writelane_b32 v254, s12, 8
	s_addc_u32 s1, s15, 0
	s_cmp_lt_i32 s54, 1
	v_writelane_b32 v254, s13, 9
	v_writelane_b32 v254, s14, 10
	v_writelane_b32 v254, s15, 11
	v_writelane_b32 v254, s0, 12
	s_nop 1
	v_writelane_b32 v254, s1, 13
	s_mov_b64 s[0:1], 0
	v_writelane_b32 v254, s8, 14
	s_cbranch_scc1 .LBB0_31
	s_cmp_eq_u32 s54, 1
	s_mov_b64 s[4:5], -1
	s_cbranch_scc0 .LBB0_30
	v_readlane_b32 s4, v254, 0
	s_cmpk_gt_i32 s4, 0x41ff
	v_readlane_b32 s5, v254, 1
	s_cbranch_scc1 .LBB0_29
	v_readlane_b32 s4, v254, 12
	v_lshlrev_b32_e32 v0, 3, v223
	v_readlane_b32 s5, v254, 13
	v_lshlrev_b32_e32 v2, 2, v223
	v_or_b32_e32 v4, 0x100, v2
	v_lshl_add_u64 v[6:7], s[4:5], 0, v[0:1]
	v_readlane_b32 s4, v254, 0
	s_mov_b32 s8, s4
	s_mov_b32 s6, s8
	v_or_b32_e32 v8, 0x200, v2
	v_or_b32_e32 v10, 0x300, v2
	v_readlane_b32 s5, v254, 1
	s_ashr_i32 s9, s4, 31
	v_writelane_b32 v254, s6, 0
	s_lshl_b64 s[4:5], s[8:9], 12
	v_lshlrev_b32_e32 v0, 2, v2
	v_lshlrev_b32_e32 v14, 2, v4
	v_lshlrev_b32_e32 v15, 2, v8
	v_lshlrev_b32_e32 v16, 2, v10
	v_writelane_b32 v254, s7, 1
	s_mov_b64 s[6:7], s[8:9]
	s_load_dwordx2 s[98:99], s[42:43], 0x0
	s_waitcnt lgkmcnt(0)
	s_branch .LBB0_16
.LBB0_15:
.LBB0_16:
	s_cmpk_gt_i32 s6, 0x3fff
	s_cbranch_scc1 .Lpa_ctx
	s_add_u32 s12, s98, s4
	s_addc_u32 s13, s99, s5
	s_branch .Lpa_src
.Lpa_ctx:
	s_load_dwordx2 s[12:13], s[42:43], 0x10
	s_add_i32 s14, s6, 0xffffc000
	s_ashr_i32 s15, s14, 31
	s_lshl_b64 s[14:15], s[14:15], 12
	s_waitcnt lgkmcnt(0)
	s_add_u32 s12, s12, s14
	s_addc_u32 s13, s13, s15
.Lpa_src:
	s_cmpk_lt_u32 s6, 0x4000
	s_cselect_b32 s10, s90, 0x3000
	s_cmpk_gt_i32 s6, 0x1fff
	s_cselect_b32 s10, s10, 0
	s_lshl_b32 s10, s10, 2
	v_readlane_b32 s16, v254, 2
	v_readlane_b32 s17, v254, 3
	s_nop 3
	s_add_u32 s16, s16, s10
	s_addc_u32 s17, s17, 0
	s_add_u32 s10, s16, 0x1000
	s_addc_u32 s11, s17, 0
	global_load_dwordx4 v[2:5], v0, s[12:13]
	global_load_dwordx4 v[26:29], v14, s[12:13]
	global_load_dwordx4 v[30:33], v15, s[12:13]
	global_load_dwordx4 v[34:37], v16, s[12:13]
	global_load_dwordx4 v[38:41], v0, s[10:11]
	global_load_dwordx4 v[42:45], v0, s[16:17]
	global_load_dwordx4 v[46:49], v14, s[10:11]
	global_load_dwordx4 v[50:53], v14, s[16:17]
	global_load_dwordx4 v[54:57], v15, s[10:11]
	global_load_dwordx4 v[58:61], v15, s[16:17]
	global_load_dwordx4 v[62:65], v16, s[10:11]
	global_load_dwordx4 v[66:69], v16, s[16:17]
	s_lshl_b64 s[14:15], s[6:7], 11
	v_lshl_add_u64 v[8:9], v[6:7], 0, s[14:15]
	s_add_u32 s6, s6, s82
	s_addc_u32 s7, s7, s83
	v_readlane_b32 s8, v253, 53
	v_readlane_b32 s9, v253, 54
	s_nop 3
	s_add_u32 s4, s4, s8
	s_addc_u32 s5, s5, s9
	s_waitcnt vmcnt(6)
	v_pk_add_f32 v[40:41], v[40:41], 1.0 op_sel_hi:[1,0]
	v_pk_add_f32 v[38:39], v[38:39], 1.0 op_sel_hi:[1,0]
	v_pk_fma_f32 v[4:5], v[4:5], v[40:41], v[44:45]
	v_pk_fma_f32 v[2:3], v[2:3], v[38:39], v[42:43]
	s_nop 0
	v_cvt_pk_bf16_f32 v2, v2, v3
	v_cvt_pk_bf16_f32 v3, v4, v5
	global_store_dwordx2 v[8:9], v[2:3], off
	s_waitcnt vmcnt(5)
	v_pk_add_f32 v[48:49], v[48:49], 1.0 op_sel_hi:[1,0]
	v_pk_add_f32 v[46:47], v[46:47], 1.0 op_sel_hi:[1,0]
	v_pk_fma_f32 v[28:29], v[28:29], v[48:49], v[52:53]
	v_pk_fma_f32 v[26:27], v[26:27], v[46:47], v[50:51]
	s_nop 0
	v_cvt_pk_bf16_f32 v26, v26, v27
	v_cvt_pk_bf16_f32 v27, v28, v29
	global_store_dwordx2 v[8:9], v[26:27], off offset:512
	s_waitcnt vmcnt(4)
	v_pk_add_f32 v[56:57], v[56:57], 1.0 op_sel_hi:[1,0]
	v_pk_add_f32 v[54:55], v[54:55], 1.0 op_sel_hi:[1,0]
	v_pk_fma_f32 v[32:33], v[32:33], v[56:57], v[60:61]
	v_pk_fma_f32 v[30:31], v[30:31], v[54:55], v[58:59]
	s_nop 0
	v_cvt_pk_bf16_f32 v30, v30, v31
	v_cvt_pk_bf16_f32 v31, v32, v33
	global_store_dwordx2 v[8:9], v[30:31], off offset:1024
	s_waitcnt vmcnt(3)
	v_pk_add_f32 v[64:65], v[64:65], 1.0 op_sel_hi:[1,0]
	v_pk_add_f32 v[62:63], v[62:63], 1.0 op_sel_hi:[1,0]
	v_pk_fma_f32 v[36:37], v[36:37], v[64:65], v[68:69]
	v_pk_fma_f32 v[34:35], v[34:35], v[62:63], v[66:67]
	s_nop 0
	v_cvt_pk_bf16_f32 v34, v34, v35
	v_cvt_pk_bf16_f32 v35, v36, v37
	global_store_dwordx2 v[8:9], v[34:35], off offset:1536
	s_cmpk_gt_i32 s6, 0x41ff
	s_cbranch_scc0 .LBB0_16
	s_branch .LBB0_29
	global_store_dwordx4 v0, v[2:5], s[8:9] offset:3072
	s_branch .LBB0_15
